# static priority raise (s_setprio 3) for the layer-1 GLA chain waves, reset at the chain loop exit
# speedup vs baseline: 1.0066x; 1.0066x over previous
; __global__ void __launch_bounds__(NTHR, 2) mega(P p) {
;     ...
;         for (int cid = vb; cid < 128; cid += (split1 ? 128 : nvb)) gla_chain_mfma(p, cid, smem);
;       __syncthreads();
;       if (!split1 || vb >= 128)
;       {
;         const u16* Q = (const u16*)(ws + OFF_QB);
;         const u16* Kb = (const u16*)(ws + OFF_KB);
;         const u16* z = (const u16*)(ws + OFF_REGB);
;         for (int it = (split1 ? vb - 128 : vb); it < 1024; it += (split1 ? nvb - 128 : nvb)) {
.LBB0_709:
	s_setprio 0
	v_readlane_b32 s0, v221, 25
	v_readlane_b32 s1, v221, 26
	s_andn2_b64 vcc, exec, s[0:1]
	s_waitcnt lgkmcnt(0)
	s_barrier
	s_cbranch_vccnz .LBB0_712
	v_readlane_b32 s0, v221, 27
	v_readlane_b32 s1, v221, 28
	s_andn2_b64 vcc, exec, s[0:1]
	v_readlane_b32 s15, v220, 59
	v_readlane_b32 s16, v220, 58
	s_cbranch_vccz .LBB0_765

; DI void gla_chain_mfma(const P& p, int cid, char* smem) {
;     ...
;   const int tid = get_tid(), lane = tid & 63, wave = tid >> 6, r = lane & 31, hh = lane >> 5;
;   const int et = wave >> 1, it = wave & 1;
;   const int pp = tid >> 2, q4 = tid & 3;
;   const u16* z = (const u16*)(p.ws + OFF_REGB);
;   const float* alpha = dir == 0 ? (const float*)(p.ws + OFF_KB + (size_t)T * 128 * 2)
;                                 : (const float*)(p.ws + OFF_REGA + (size_t)LAT * 512 * 2);
;   u16* od = (u16*)(p.ws + OFF_ODIR) + (size_t)dir * T * 512;
;   __syncthreads();
;   for (int i = tid; i < 64 * 72 / 2; i += NTHR) ((unsigned*)ST)[i] = 0u;
;   f32x16 Sreg;
; #pragma unroll
;   for (int i = 0; i < 16; ++i) Sreg[i] = 0.f;
;   __syncthreads();
.LBB0_716:
	s_setprio 3
	v_mov_b32_e32 v17, v132
	s_movk_i32 s0, 0x8ff
	s_nop 0
	v_cmp_lt_i32_e32 vcc, s0, v17
	v_lshlrev_b32_e32 v16, 2, v17
	s_barrier
	s_and_saveexec_b64 s[0:1], vcc
	s_xor_b64 s[0:1], exec, s[0:1]
	v_lshlrev_b32_e32 v16, 2, v17
	s_andn2_saveexec_b64 s[0:1], s[0:1]
	s_cbranch_execz .LBB0_722
	s_add_i32 s4, 0, 0x9000
	s_waitcnt vmcnt(3)
	v_add_u32_e32 v0, s4, v16
	v_add_u32_e32 v1, 0xffffff00, v17
	s_mov_b64 s[4:5], 0
